# decode-merge phase: w_uv mat-vec loop software-pipelined (next 32 loads issued before the current 32 are consumed, second register set), FMA order unchanged
# baseline (speedup 1.0000x reference)
.LBB0_1018:
	v_add_co_u32_e32 v10, vcc, 0x1000, v4
	global_load_dword v8, v[4:5], off
	s_nop 0
	v_addc_co_u32_e32 v11, vcc, 0, v5, vcc
	global_load_dword v9, v[10:11], off
	v_add_co_u32_e32 v10, vcc, 0x2000, v4
	s_mov_b32 s1, 0xf000
	s_nop 0
	v_addc_co_u32_e32 v11, vcc, 0, v5, vcc
	v_add_co_u32_e32 v12, vcc, 0x3000, v4
	global_load_dword v10, v[10:11], off
	s_nop 0
	v_addc_co_u32_e32 v13, vcc, 0, v5, vcc
	global_load_dword v11, v[12:13], off
	v_add_co_u32_e32 v12, vcc, 0x4000, v4
	s_nop 0
	v_addc_co_u32_e32 v13, vcc, 0, v5, vcc
	v_add_co_u32_e32 v14, vcc, 0x5000, v4
	global_load_dword v12, v[12:13], off
	s_nop 0
	v_addc_co_u32_e32 v15, vcc, 0, v5, vcc
	global_load_dword v13, v[14:15], off
	v_add_co_u32_e32 v14, vcc, 0x6000, v4
	s_nop 0
	v_addc_co_u32_e32 v15, vcc, 0, v5, vcc
	v_add_co_u32_e32 v16, vcc, 0x7000, v4
	global_load_dword v14, v[14:15], off
	s_nop 0
	v_addc_co_u32_e32 v17, vcc, 0, v5, vcc
	global_load_dword v15, v[16:17], off
	v_add_co_u32_e32 v16, vcc, s33, v4
	s_nop 1
	v_addc_co_u32_e32 v17, vcc, 0, v5, vcc
	v_add_co_u32_e32 v18, vcc, 0x9000, v4
	global_load_dword v16, v[16:17], off
	s_nop 0
	v_addc_co_u32_e32 v19, vcc, 0, v5, vcc
	global_load_dword v17, v[18:19], off
	v_add_co_u32_e32 v18, vcc, s94, v4
	s_nop 1
	v_addc_co_u32_e32 v19, vcc, 0, v5, vcc
	v_add_co_u32_e32 v20, vcc, 0xb000, v4
	global_load_dword v18, v[18:19], off
	s_nop 0
	v_addc_co_u32_e32 v21, vcc, 0, v5, vcc
	global_load_dword v19, v[20:21], off
	v_add_co_u32_e32 v20, vcc, s87, v4
	s_nop 1
	v_addc_co_u32_e32 v21, vcc, 0, v5, vcc
	v_add_co_u32_e32 v22, vcc, 0xd000, v4
	global_load_dword v20, v[20:21], off
	s_nop 0
	v_addc_co_u32_e32 v23, vcc, 0, v5, vcc
	global_load_dword v21, v[22:23], off
	v_add_co_u32_e32 v22, vcc, s1, v4
	s_mov_b32 s1, 0x11000
	s_nop 0
	v_addc_co_u32_e32 v23, vcc, 0, v5, vcc
	global_load_dword v26, v[22:23], off offset:-4096
	global_load_dword v27, v[22:23], off
	v_add_co_u32_e32 v24, vcc, s1, v4
	s_mov_b32 s1, 0x13000
	s_nop 0
	v_addc_co_u32_e32 v25, vcc, 0, v5, vcc
	v_add_co_u32_e32 v28, vcc, s1, v4
	global_load_dword v22, v[24:25], off offset:-4096
	global_load_dword v23, v[24:25], off
	v_addc_co_u32_e32 v29, vcc, 0, v5, vcc
	global_load_dword v24, v[28:29], off offset:-4096
	global_load_dword v25, v[28:29], off
	s_mov_b32 s1, 0x15000
	v_add_co_u32_e32 v30, vcc, s1, v4
	s_mov_b32 s1, 0x17000
	s_nop 0
	v_addc_co_u32_e32 v31, vcc, 0, v5, vcc
	v_add_co_u32_e32 v32, vcc, s1, v4
	global_load_dword v28, v[30:31], off offset:-4096
	global_load_dword v29, v[30:31], off
	v_addc_co_u32_e32 v33, vcc, 0, v5, vcc
	global_load_dword v30, v[32:33], off offset:-4096
	global_load_dword v31, v[32:33], off
	s_mov_b32 s1, 0x19000
	v_add_co_u32_e32 v34, vcc, s1, v4
	s_mov_b32 s1, 0x1b000
	s_nop 0
	v_addc_co_u32_e32 v35, vcc, 0, v5, vcc
	v_add_co_u32_e32 v36, vcc, s1, v4
	global_load_dword v32, v[34:35], off offset:-4096
	global_load_dword v33, v[34:35], off
	v_addc_co_u32_e32 v37, vcc, 0, v5, vcc
	global_load_dword v34, v[36:37], off offset:-4096
	global_load_dword v35, v[36:37], off
	s_mov_b32 s1, 0x1d000
	v_add_co_u32_e32 v38, vcc, s1, v4
	s_mov_b32 s1, 0x1f000
	s_nop 0
	v_addc_co_u32_e32 v39, vcc, 0, v5, vcc
	global_load_dword v36, v[38:39], off offset:-4096
	global_load_dword v37, v[38:39], off
	v_add_co_u32_e32 v38, vcc, s1, v4
	s_nop 1
	v_addc_co_u32_e32 v39, vcc, 0, v5, vcc
	global_load_dword v54, v[38:39], off offset:-4096
	global_load_dword v55, v[38:39], off
	v_lshl_add_u64 v[4:5], v[4:5], 0, s[72:73]
	s_mov_b32 s100, 3
.Lcmb_loop:
	v_add_co_u32_e32 v232, vcc, 0x1000, v4
	global_load_dword v230, v[4:5], off
	s_nop 0
	v_addc_co_u32_e32 v233, vcc, 0, v5, vcc
	global_load_dword v231, v[232:233], off
	v_add_co_u32_e32 v232, vcc, 0x2000, v4
	s_mov_b32 s1, 0xf000
	s_nop 0
	v_addc_co_u32_e32 v233, vcc, 0, v5, vcc
	v_add_co_u32_e32 v234, vcc, 0x3000, v4
	global_load_dword v232, v[232:233], off
	s_nop 0
	v_addc_co_u32_e32 v235, vcc, 0, v5, vcc
	global_load_dword v233, v[234:235], off
	v_add_co_u32_e32 v234, vcc, 0x4000, v4
	s_nop 0
	v_addc_co_u32_e32 v235, vcc, 0, v5, vcc
	v_add_co_u32_e32 v236, vcc, 0x5000, v4
	global_load_dword v234, v[234:235], off
	s_nop 0
	v_addc_co_u32_e32 v237, vcc, 0, v5, vcc
	global_load_dword v235, v[236:237], off
	v_add_co_u32_e32 v236, vcc, 0x6000, v4
	s_nop 0
	v_addc_co_u32_e32 v237, vcc, 0, v5, vcc
	v_add_co_u32_e32 v238, vcc, 0x7000, v4
	global_load_dword v236, v[236:237], off
	s_nop 0
	v_addc_co_u32_e32 v239, vcc, 0, v5, vcc
	global_load_dword v237, v[238:239], off
	v_add_co_u32_e32 v238, vcc, s33, v4
	s_nop 1
	v_addc_co_u32_e32 v239, vcc, 0, v5, vcc
	v_add_co_u32_e32 v240, vcc, 0x9000, v4
	global_load_dword v238, v[238:239], off
	s_nop 0
	v_addc_co_u32_e32 v241, vcc, 0, v5, vcc
	global_load_dword v239, v[240:241], off
	v_add_co_u32_e32 v240, vcc, s94, v4
	s_nop 1
	v_addc_co_u32_e32 v241, vcc, 0, v5, vcc
	v_add_co_u32_e32 v242, vcc, 0xb000, v4
	global_load_dword v240, v[240:241], off
	s_nop 0
	v_addc_co_u32_e32 v243, vcc, 0, v5, vcc
	global_load_dword v241, v[242:243], off
	v_add_co_u32_e32 v242, vcc, s87, v4
	s_nop 1
	v_addc_co_u32_e32 v243, vcc, 0, v5, vcc
	v_add_co_u32_e32 v244, vcc, 0xd000, v4
	global_load_dword v242, v[242:243], off
	s_nop 0
	v_addc_co_u32_e32 v245, vcc, 0, v5, vcc
	global_load_dword v243, v[244:245], off
	v_add_co_u32_e32 v244, vcc, s1, v4
	s_mov_b32 s1, 0x11000
	s_nop 0
	v_addc_co_u32_e32 v245, vcc, 0, v5, vcc
	global_load_dword v248, v[244:245], off offset:-4096
	global_load_dword v249, v[244:245], off
	v_add_co_u32_e32 v246, vcc, s1, v4
	s_mov_b32 s1, 0x13000
	s_nop 0
	v_addc_co_u32_e32 v247, vcc, 0, v5, vcc
	v_add_co_u32_e32 v250, vcc, s1, v4
	global_load_dword v244, v[246:247], off offset:-4096
	global_load_dword v245, v[246:247], off
	v_addc_co_u32_e32 v251, vcc, 0, v5, vcc
	global_load_dword v246, v[250:251], off offset:-4096
	global_load_dword v247, v[250:251], off
	s_mov_b32 s1, 0x15000
	v_add_co_u32_e32 v252, vcc, s1, v4
	s_mov_b32 s1, 0x17000
	s_nop 0
	v_addc_co_u32_e32 v253, vcc, 0, v5, vcc
	v_add_co_u32_e32 v56, vcc, s1, v4
	global_load_dword v250, v[252:253], off offset:-4096
	global_load_dword v251, v[252:253], off
	v_addc_co_u32_e32 v57, vcc, 0, v5, vcc
	global_load_dword v252, v[56:57], off offset:-4096
	global_load_dword v253, v[56:57], off
	s_mov_b32 s1, 0x19000
	v_add_co_u32_e32 v58, vcc, s1, v4
	s_mov_b32 s1, 0x1b000
	s_nop 0
	v_addc_co_u32_e32 v59, vcc, 0, v5, vcc
	v_add_co_u32_e32 v60, vcc, s1, v4
	global_load_dword v56, v[58:59], off offset:-4096
	global_load_dword v57, v[58:59], off
	v_addc_co_u32_e32 v61, vcc, 0, v5, vcc
	global_load_dword v58, v[60:61], off offset:-4096
	global_load_dword v59, v[60:61], off
	s_mov_b32 s1, 0x1d000
	v_add_co_u32_e32 v68, vcc, s1, v4
	s_mov_b32 s1, 0x1f000
	s_nop 0
	v_addc_co_u32_e32 v69, vcc, 0, v5, vcc
	global_load_dword v60, v[68:69], off offset:-4096
	global_load_dword v61, v[68:69], off
	v_add_co_u32_e32 v68, vcc, s1, v4
	s_nop 1
	v_addc_co_u32_e32 v69, vcc, 0, v5, vcc
	global_load_dword v80, v[68:69], off offset:-4096
	global_load_dword v81, v[68:69], off
	v_lshl_add_u64 v[4:5], v[4:5], 0, s[72:73]
	ds_read_b128 v[38:41], v3
	ds_read_b128 v[42:45], v3 offset:16
	ds_read_b128 v[46:49], v3 offset:32
	ds_read_b128 v[50:53], v3 offset:48
	s_waitcnt vmcnt(62) lgkmcnt(3)
	v_pk_fma_f32 v[6:7], v[8:9], v[38:39], v[6:7]
	s_waitcnt vmcnt(60)
	v_pk_fma_f32 v[6:7], v[10:11], v[40:41], v[6:7]
	s_waitcnt vmcnt(58) lgkmcnt(2)
	v_pk_fma_f32 v[6:7], v[12:13], v[42:43], v[6:7]
	s_waitcnt vmcnt(56)
	v_pk_fma_f32 v[6:7], v[14:15], v[44:45], v[6:7]
	s_waitcnt vmcnt(54) lgkmcnt(1)
	v_pk_fma_f32 v[6:7], v[16:17], v[46:47], v[6:7]
	s_waitcnt vmcnt(52)
	v_pk_fma_f32 v[6:7], v[18:19], v[48:49], v[6:7]
	s_waitcnt vmcnt(50) lgkmcnt(0)
	v_pk_fma_f32 v[6:7], v[20:21], v[50:51], v[6:7]
	s_waitcnt vmcnt(48)
	v_pk_fma_f32 v[10:11], v[26:27], v[52:53], v[6:7]
	ds_read_b128 v[6:9], v3 offset:64
	s_waitcnt vmcnt(46) lgkmcnt(0)
	v_pk_fma_f32 v[6:7], v[22:23], v[6:7], v[10:11]
	s_waitcnt vmcnt(44)
	v_pk_fma_f32 v[10:11], v[24:25], v[8:9], v[6:7]
	ds_read_b128 v[6:9], v3 offset:80
	s_waitcnt vmcnt(42) lgkmcnt(0)
	v_pk_fma_f32 v[6:7], v[28:29], v[6:7], v[10:11]
	s_waitcnt vmcnt(40)
	v_pk_fma_f32 v[10:11], v[30:31], v[8:9], v[6:7]
	ds_read_b128 v[6:9], v3 offset:96
	s_waitcnt vmcnt(38) lgkmcnt(0)
	v_pk_fma_f32 v[6:7], v[32:33], v[6:7], v[10:11]
	s_waitcnt vmcnt(36)
	v_pk_fma_f32 v[10:11], v[34:35], v[8:9], v[6:7]
	ds_read_b128 v[6:9], v3 offset:112
	v_add_u32_e32 v3, 0x80, v3
	s_waitcnt vmcnt(34) lgkmcnt(0)
	v_pk_fma_f32 v[6:7], v[36:37], v[6:7], v[10:11]
	s_waitcnt vmcnt(32)
	v_pk_fma_f32 v[6:7], v[54:55], v[8:9], v[6:7]
	s_cmp_eq_u32 s100, 0
	s_cbranch_scc1 .Lcmb_tail
	v_add_co_u32_e32 v10, vcc, 0x1000, v4
	global_load_dword v8, v[4:5], off
	s_nop 0
	v_addc_co_u32_e32 v11, vcc, 0, v5, vcc
	global_load_dword v9, v[10:11], off
	v_add_co_u32_e32 v10, vcc, 0x2000, v4
	s_mov_b32 s1, 0xf000
	s_nop 0
	v_addc_co_u32_e32 v11, vcc, 0, v5, vcc
	v_add_co_u32_e32 v12, vcc, 0x3000, v4
	global_load_dword v10, v[10:11], off
	s_nop 0
	v_addc_co_u32_e32 v13, vcc, 0, v5, vcc
	global_load_dword v11, v[12:13], off
	v_add_co_u32_e32 v12, vcc, 0x4000, v4
	s_nop 0
	v_addc_co_u32_e32 v13, vcc, 0, v5, vcc
	v_add_co_u32_e32 v14, vcc, 0x5000, v4
	global_load_dword v12, v[12:13], off
	s_nop 0
	v_addc_co_u32_e32 v15, vcc, 0, v5, vcc
	global_load_dword v13, v[14:15], off
	v_add_co_u32_e32 v14, vcc, 0x6000, v4
	s_nop 0
	v_addc_co_u32_e32 v15, vcc, 0, v5, vcc
	v_add_co_u32_e32 v16, vcc, 0x7000, v4
	global_load_dword v14, v[14:15], off
	s_nop 0
	v_addc_co_u32_e32 v17, vcc, 0, v5, vcc
	global_load_dword v15, v[16:17], off
	v_add_co_u32_e32 v16, vcc, s33, v4
	s_nop 1
	v_addc_co_u32_e32 v17, vcc, 0, v5, vcc
	v_add_co_u32_e32 v18, vcc, 0x9000, v4
	global_load_dword v16, v[16:17], off
	s_nop 0
	v_addc_co_u32_e32 v19, vcc, 0, v5, vcc
	global_load_dword v17, v[18:19], off
	v_add_co_u32_e32 v18, vcc, s94, v4
	s_nop 1
	v_addc_co_u32_e32 v19, vcc, 0, v5, vcc
	v_add_co_u32_e32 v20, vcc, 0xb000, v4
	global_load_dword v18, v[18:19], off
	s_nop 0
	v_addc_co_u32_e32 v21, vcc, 0, v5, vcc
	global_load_dword v19, v[20:21], off
	v_add_co_u32_e32 v20, vcc, s87, v4
	s_nop 1
	v_addc_co_u32_e32 v21, vcc, 0, v5, vcc
	v_add_co_u32_e32 v22, vcc, 0xd000, v4
	global_load_dword v20, v[20:21], off
	s_nop 0
	v_addc_co_u32_e32 v23, vcc, 0, v5, vcc
	global_load_dword v21, v[22:23], off
	v_add_co_u32_e32 v22, vcc, s1, v4
	s_mov_b32 s1, 0x11000
	s_nop 0
	v_addc_co_u32_e32 v23, vcc, 0, v5, vcc
	global_load_dword v26, v[22:23], off offset:-4096
	global_load_dword v27, v[22:23], off
	v_add_co_u32_e32 v24, vcc, s1, v4
	s_mov_b32 s1, 0x13000
	s_nop 0
	v_addc_co_u32_e32 v25, vcc, 0, v5, vcc
	v_add_co_u32_e32 v28, vcc, s1, v4
	global_load_dword v22, v[24:25], off offset:-4096
	global_load_dword v23, v[24:25], off
	v_addc_co_u32_e32 v29, vcc, 0, v5, vcc
	global_load_dword v24, v[28:29], off offset:-4096
	global_load_dword v25, v[28:29], off
	s_mov_b32 s1, 0x15000
	v_add_co_u32_e32 v30, vcc, s1, v4
	s_mov_b32 s1, 0x17000
	s_nop 0
	v_addc_co_u32_e32 v31, vcc, 0, v5, vcc
	v_add_co_u32_e32 v32, vcc, s1, v4
	global_load_dword v28, v[30:31], off offset:-4096
	global_load_dword v29, v[30:31], off
	v_addc_co_u32_e32 v33, vcc, 0, v5, vcc
	global_load_dword v30, v[32:33], off offset:-4096
	global_load_dword v31, v[32:33], off
	s_mov_b32 s1, 0x19000
	v_add_co_u32_e32 v34, vcc, s1, v4
	s_mov_b32 s1, 0x1b000
	s_nop 0
	v_addc_co_u32_e32 v35, vcc, 0, v5, vcc
	v_add_co_u32_e32 v36, vcc, s1, v4
	global_load_dword v32, v[34:35], off offset:-4096
	global_load_dword v33, v[34:35], off
	v_addc_co_u32_e32 v37, vcc, 0, v5, vcc
	global_load_dword v34, v[36:37], off offset:-4096
	global_load_dword v35, v[36:37], off
	s_mov_b32 s1, 0x1d000
	v_add_co_u32_e32 v38, vcc, s1, v4
	s_mov_b32 s1, 0x1f000
	s_nop 0
	v_addc_co_u32_e32 v39, vcc, 0, v5, vcc
	global_load_dword v36, v[38:39], off offset:-4096
	global_load_dword v37, v[38:39], off
	v_add_co_u32_e32 v38, vcc, s1, v4
	s_nop 1
	v_addc_co_u32_e32 v39, vcc, 0, v5, vcc
	global_load_dword v54, v[38:39], off offset:-4096
	global_load_dword v55, v[38:39], off
	v_lshl_add_u64 v[4:5], v[4:5], 0, s[72:73]
	v_mov_b64_e32 v[228:229], v[6:7]
	ds_read_b128 v[68:71], v3
	ds_read_b128 v[72:75], v3 offset:16
	ds_read_b128 v[76:79], v3 offset:32
	ds_read_b128 v[62:65], v3 offset:48
	s_waitcnt vmcnt(62) lgkmcnt(3)
	v_pk_fma_f32 v[228:229], v[230:231], v[68:69], v[228:229]
	s_waitcnt vmcnt(60)
	v_pk_fma_f32 v[228:229], v[232:233], v[70:71], v[228:229]
	s_waitcnt vmcnt(58) lgkmcnt(2)
	v_pk_fma_f32 v[228:229], v[234:235], v[72:73], v[228:229]
	s_waitcnt vmcnt(56)
	v_pk_fma_f32 v[228:229], v[236:237], v[74:75], v[228:229]
	s_waitcnt vmcnt(54) lgkmcnt(1)
	v_pk_fma_f32 v[228:229], v[238:239], v[76:77], v[228:229]
	s_waitcnt vmcnt(52)
	v_pk_fma_f32 v[228:229], v[240:241], v[78:79], v[228:229]
	s_waitcnt vmcnt(50) lgkmcnt(0)
	v_pk_fma_f32 v[228:229], v[242:243], v[62:63], v[228:229]
	s_waitcnt vmcnt(48)
	v_pk_fma_f32 v[232:233], v[248:249], v[64:65], v[228:229]
	ds_read_b128 v[228:231], v3 offset:64
	s_waitcnt vmcnt(46) lgkmcnt(0)
	v_pk_fma_f32 v[228:229], v[244:245], v[228:229], v[232:233]
	s_waitcnt vmcnt(44)
	v_pk_fma_f32 v[232:233], v[246:247], v[230:231], v[228:229]
	ds_read_b128 v[228:231], v3 offset:80
	s_waitcnt vmcnt(42) lgkmcnt(0)
	v_pk_fma_f32 v[228:229], v[250:251], v[228:229], v[232:233]
	s_waitcnt vmcnt(40)
	v_pk_fma_f32 v[232:233], v[252:253], v[230:231], v[228:229]
	ds_read_b128 v[228:231], v3 offset:96
	s_waitcnt vmcnt(38) lgkmcnt(0)
	v_pk_fma_f32 v[228:229], v[56:57], v[228:229], v[232:233]
	s_waitcnt vmcnt(36)
	v_pk_fma_f32 v[232:233], v[58:59], v[230:231], v[228:229]
	ds_read_b128 v[228:231], v3 offset:112
	v_add_u32_e32 v3, 0x80, v3
	s_waitcnt vmcnt(34) lgkmcnt(0)
	v_pk_fma_f32 v[228:229], v[60:61], v[228:229], v[232:233]
	s_waitcnt vmcnt(32)
	v_pk_fma_f32 v[228:229], v[80:81], v[230:231], v[228:229]
	v_mov_b64_e32 v[6:7], v[228:229]
	s_add_i32 s100, s100, -1
	s_branch .Lcmb_loop
.Lcmb_tail:
	v_mov_b64_e32 v[228:229], v[6:7]
	ds_read_b128 v[68:71], v3
	ds_read_b128 v[72:75], v3 offset:16
	ds_read_b128 v[76:79], v3 offset:32
	ds_read_b128 v[62:65], v3 offset:48
	s_waitcnt vmcnt(30) lgkmcnt(3)
	v_pk_fma_f32 v[228:229], v[230:231], v[68:69], v[228:229]
	s_waitcnt vmcnt(28)
	v_pk_fma_f32 v[228:229], v[232:233], v[70:71], v[228:229]
	s_waitcnt vmcnt(26) lgkmcnt(2)
	v_pk_fma_f32 v[228:229], v[234:235], v[72:73], v[228:229]
	s_waitcnt vmcnt(24)
	v_pk_fma_f32 v[228:229], v[236:237], v[74:75], v[228:229]
	s_waitcnt vmcnt(22) lgkmcnt(1)
	v_pk_fma_f32 v[228:229], v[238:239], v[76:77], v[228:229]
	s_waitcnt vmcnt(20)
	v_pk_fma_f32 v[228:229], v[240:241], v[78:79], v[228:229]
	s_waitcnt vmcnt(18) lgkmcnt(0)
	v_pk_fma_f32 v[228:229], v[242:243], v[62:63], v[228:229]
	s_waitcnt vmcnt(16)
	v_pk_fma_f32 v[232:233], v[248:249], v[64:65], v[228:229]
	ds_read_b128 v[228:231], v3 offset:64
	s_waitcnt vmcnt(14) lgkmcnt(0)
	v_pk_fma_f32 v[228:229], v[244:245], v[228:229], v[232:233]
	s_waitcnt vmcnt(12)
	v_pk_fma_f32 v[232:233], v[246:247], v[230:231], v[228:229]
	ds_read_b128 v[228:231], v3 offset:80
	s_waitcnt vmcnt(10) lgkmcnt(0)
	v_pk_fma_f32 v[228:229], v[250:251], v[228:229], v[232:233]
	s_waitcnt vmcnt(8)
	v_pk_fma_f32 v[232:233], v[252:253], v[230:231], v[228:229]
	ds_read_b128 v[228:231], v3 offset:96
	s_waitcnt vmcnt(6) lgkmcnt(0)
	v_pk_fma_f32 v[228:229], v[56:57], v[228:229], v[232:233]
	s_waitcnt vmcnt(4)
	v_pk_fma_f32 v[232:233], v[58:59], v[230:231], v[228:229]
	ds_read_b128 v[228:231], v3 offset:112
	v_add_u32_e32 v3, 0x80, v3
	s_waitcnt vmcnt(2) lgkmcnt(0)
	v_pk_fma_f32 v[228:229], v[60:61], v[228:229], v[232:233]
	s_waitcnt vmcnt(0)
	v_pk_fma_f32 v[228:229], v[80:81], v[230:231], v[228:229]
	v_mov_b64_e32 v[6:7], v[228:229]
	v_pk_add_f32 v[4:5], v[6:7], v[6:7] op_sel:[0,1] op_sel_hi:[1,0]
	s_ashr_i32 s9, s8, 31
	v_bfe_u32 v3, v4, 16, 1
	s_lshl_b64 s[0:1], s[8:9], 11
	v_add3_u32 v3, v4, v3, s48
	v_and_b32_e32 v4, 0xffffff80, v1
	s_add_u32 s0, s13, s0
	v_ashrrev_i32_e32 v5, 31, v4
	s_addc_u32 s1, s14, s1
	v_lshl_add_u64 v[4:5], v[4:5], 1, s[0:1]
	v_lshlrev_b32_e32 v0, 1, v0
	v_mov_b32_e32 v1, v2
	v_lshl_add_u64 v[0:1], v[4:5], 0, v[0:1]
	v_add_co_u32_e32 v0, vcc, 0x4008000, v0
	s_add_i32 s3, s3, s2
	s_xor_b64 s[4:5], s[4:5], s[6:7]
	v_addc_co_u32_e32 v1, vcc, 0, v1, vcc
	s_cmpk_gt_i32 s3, 0xff
	global_store_short_d16_hi v[0:1], v3, off
	s_barrier
	s_cbranch_scc0 .LBB0_1015
